# stack v82 + hgrn pass-0 step: the four state tiles' LDS fragment reads issued together after the barrier into own registers with counted waits (was read / full wait / MFMA per tile)
# baseline (speedup 1.0000x reference)
; #define LAS __attribute__((address_space(3)))
; __device__ __forceinline__ unsigned pk2(float lo, float hi) { unsigned r; asm("v_cvt_pk_bf16_f32 %0, %1, %2" : "=v"(r) : "v"(lo), "v"(hi)); return r; }
; __device__ __forceinline__ f32x4 mfma16(bf16x8 a, bf16x8 b, f32x4 c) { return __builtin_amdgcn_mfma_f32_16x16x32_bf16(a, b, c, 0, 0, 0); }
; __device__ __forceinline__ void lds_barrier() { asm volatile("s_waitcnt lgkmcnt(0)" ::: "memory"); __builtin_amdgcn_s_barrier(); asm volatile("" ::: "memory"); }
; __device__ __forceinline__ void hgrn_item(const Params& p, int l, int item, int pass, LAS unsigned char* lds) {
;     ...
;         lds_barrier();
;         f32x4 o = ZERO4;
;         if (pass == 1) {
;             const bf16x8 ka0 = *(const LAS bf16x8*)(Ks + fr * 72 + fq * 8), ka1 = *(const LAS bf16x8*)(Ks + fr * 72 + 32 + fq * 8);
;             const bf16x8 qb0 = *(const LAS bf16x8*)(Qs + fr * 72 + fq * 8), qb1 = *(const LAS bf16x8*)(Qs + fr * 72 + 32 + fq * 8);
;             f32x4 sc = mfma16(ka0, qb0, ZERO4); sc = mfma16(ka1, qb1, sc);
; #pragma unroll
;             for (int j = 0; j < 4; ++j) sc[j] = (fq * 4 + j <= fr) ? sc[j] : 0.f;
;             u32x4 pw; pw.x = pk2(sc[0], sc[1]); pw.y = pk2(sc[2], sc[3]); pw.z = 0u; pw.w = 0u;
;             o = mfma16(vfrag, as_bf8(pw), o);
; #pragma unroll
;             for (int kk = 0; kk < 2; ++kk) {
;                 u32x4 sw; sw.x = pk2(S[2 * kk][0], S[2 * kk][1]); sw.y = pk2(S[2 * kk][2], S[2 * kk][3]); sw.z = pk2(S[2 * kk + 1][0], S[2 * kk + 1][1]); sw.w = pk2(S[2 * kk + 1][2], S[2 * kk + 1][3]);
;                 const u32x2 q0 = *(const LAS u32x2*)(Qs + fr * 72 + (2 * kk) * 16 + fq * 4), q1 = *(const LAS u32x2*)(Qs + fr * 72 + (2 * kk + 1) * 16 + fq * 4);
;                 u32x4 qw; qw.x = q0.x; qw.y = q0.y; qw.z = q1.x; qw.w = q1.y;
;                 o = mfma16(as_bf8(sw), as_bf8(qw), o);
;             }
;         }
; #pragma unroll
;         for (int kt = 0; kt < 4; ++kt) { const u32x2 kh = *(const LAS u32x2*)(KHt + (kt * 16 + fr) * 16 + fq * 4); u32x4 kw; kw.x = kh.x; kw.y = kh.y; kw.z = 0u; kw.w = 0u;
;             const f32x4 dv = *(const LAS f32x4*)(decs + kt * 16 + fq * 4); S[kt] = mfma16(as_bf8(kw), vfrag, S[kt] * dv); }
.LBB0_419:
	s_or_b64 exec, exec, s[8:9]
	s_waitcnt lgkmcnt(0)
	s_barrier
	v_add_f32_e32 v30, v30, v54
	ds_read2st64_b64 v[54:57], v32 offset0:9 offset1:10
	s_waitcnt vmcnt(8)
	v_lshl_or_b32 v1, v41, 16, v1
	v_add_u32_e32 v41, v43, v42
	ds_read_b128 v[62:65], v41 offset:6656
	ds_read_b128 v[100:103], v41 offset:6720
	ds_read_b64 v[116:117], v32 offset:5632
	ds_read_b128 v[104:107], v41 offset:6784
	ds_read_b64 v[120:121], v31 offset:4608
	ds_read_b128 v[108:111], v41 offset:6848
	v_mov_b32_e32 v118, v2
	v_mov_b32_e32 v119, v2
	v_mov_b32_e32 v122, v2
	v_mov_b32_e32 v123, v2
	v_mov_b32_e32 v60, v2
	s_waitcnt lgkmcnt(6)
	v_mov_b32_e32 v58, v54
	v_mov_b32_e32 v59, v55
	v_mov_b32_e32 v61, v2
	v_lshl_or_b32 v0, v3, 16, v0
	v_mov_b32_e32 v3, v2
	s_waitcnt lgkmcnt(5)
	v_pk_mul_f32 v[16:17], v[16:17], v[62:63]
	v_pk_mul_f32 v[18:19], v[18:19], v[64:65]
	v_mov_b32_e32 v54, v56
	v_mov_b32_e32 v55, v57
	v_mfma_f32_16x16x32_bf16 v[16:19], v[58:61], v[0:3], v[16:19]
	v_mov_b32_e32 v56, v2
	v_mov_b32_e32 v57, v2
	s_add_u32 s28, s28, 0x16000
	s_addc_u32 s29, s29, 0
	s_waitcnt lgkmcnt(4)
	v_pk_mul_f32 v[12:13], v[12:13], v[100:101]
	v_pk_mul_f32 v[14:15], v[14:15], v[102:103]
	s_waitcnt vmcnt(7)
	v_and_b32_e32 v52, 0xffff, v44
	s_waitcnt vmcnt(6)
	v_and_b32_e32 v44, 0xffff, v45
	v_mfma_f32_16x16x32_bf16 v[12:15], v[54:57], v[0:3], v[12:15]
	s_waitcnt vmcnt(5)
	v_and_b32_e32 v53, 0xffff, v46
	s_waitcnt vmcnt(4)
	v_and_b32_e32 v45, 0xffff, v47
	s_waitcnt vmcnt(3)
	v_and_b32_e32 v48, 0xffff, v48
	s_waitcnt vmcnt(2)
	v_and_b32_e32 v46, 0xffff, v49
	s_waitcnt lgkmcnt(2)
	v_pk_mul_f32 v[8:9], v[8:9], v[104:105]
	v_pk_mul_f32 v[10:11], v[10:11], v[106:107]
	s_waitcnt vmcnt(1)
	v_and_b32_e32 v49, 0xffff, v50
	s_waitcnt vmcnt(0)
	v_and_b32_e32 v47, 0xffff, v51
	v_mfma_f32_16x16x32_bf16 v[8:11], v[116:119], v[0:3], v[8:11]
	s_cmp_eq_u32 s28, 0x9a000
	s_waitcnt lgkmcnt(0)
	v_pk_mul_f32 v[4:5], v[4:5], v[108:109]
	v_pk_mul_f32 v[6:7], v[6:7], v[110:111]
	s_nop 1
	v_mfma_f32_16x16x32_bf16 v[4:7], v[120:123], v[0:3], v[4:7]
	s_cbranch_scc1 .LBB0_421
	v_mov_b32_e32 v41, v47
	v_mov_b32_e32 v1, v46
	v_mov_b32_e32 v3, v45
	v_mov_b32_e32 v0, v44
	s_branch .LBB0_417
